# DSA: software-pipelined fast path for full stages + 2-stage-deep K/V/mask prefetch; index score loop wait placement
# speedup vs baseline: 1.0147x; 1.0147x over previous
; DI float bf2f(unsigned short h) { return __uint_as_float(((unsigned)h) << 16); }
; DI void index_unit(Frame& F, int b, int t0) {
;     ...
;     __syncthreads();
;     const int rg = r >> 3, rhh = (r >> 2) & 1, rc = r & 3, a_tq = 2 * rhh + (rg >> 1), a_hd = 4 * (rg & 1) + rc;
;     bf16x8 qa[2][4]; float wv[2][16];
; #pragma unroll
;     for (int mt = 0; mt < 2; ++mt) {
;         const bf16* qp = H0 + (size_t)(b * SEQ + t0 + 4 * mt + a_tq) * EVEN_LD + C_QI + a_hd * 64 + 8 * hf;
; #pragma unroll
;         for (int st = 0; st < 4; ++st) qa[mt][st] = *(const bf16x8*)(qp + 16 * st);
; #pragma unroll
;         for (int q = 0; q < 2; ++q) {
;             const bf16* wp = H0 + (size_t)(b * SEQ + t0 + 4 * mt + 2 * hf + q) * EVEN_LD + C_WI;
;             const u32x4 wr = *(const u32x4*)wp;
; #pragma unroll
;             for (int k = 0; k < 4; ++k) { const unsigned u = wr[k]; wv[mt][8 * q + 2 * k] = bf2f((unsigned short)(u & 0xffff)) * 0.04419417382415922f; wv[mt][8 * q + 2 * k + 1] = bf2f((unsigned short)(u >> 16)) * 0.04419417382415922f; }
;         }
;     }
;     const int nkt = (t0 + 8 + 31) >> 5;
;     if (t0 + 8 > 256) for (int _r22 = 0; _r22 < (PROBE_PHASE == 22 ? 2 : 1); ++_r22) {
;         bf16x8 kb[4], kn[4];
;         { const bf16* kp = H0 + (size_t)(b * SEQ + 32 * w + r) * EVEN_LD + C_KI + 8 * hf;
;           if (w < nkt) {
; #pragma unroll
;               for (int st = 0; st < 4; ++st) kb[st] = *(const bf16x8*)(kp + 16 * st); } }
.LBB0_209:
	s_bitcmp0_b32 s30, 0
	s_cselect_b32 s1, s84, s29
	s_add_i32 s1, s1, s0
	s_cmpk_gt_i32 s1, 0x7ff
	s_cbranch_scc1 .LBB0_208
	s_lshl_b32 s0, s1, 1
	s_and_b32 s0, s0, -8
	s_lshl_b32 s1, s1, 12
	s_sub_i32 s4, 0xff8, s0
	s_and_b32 s31, s1, 0x3000
	s_cmpk_lt_u32 s4, 0xf9
	s_waitcnt vmcnt(0) lgkmcnt(0)
	s_barrier
	s_cbranch_scc1 .LBB0_216
	s_sub_i32 s0, 0x1018, s0
	s_lshr_b32 s5, s0, 5
	s_cmp_ge_u32 s82, s5
	s_cbranch_scc1 .LBB0_216
	s_add_i32 s6, s4, s31
	v_or_b32_e32 v2, s6, v90
	v_mov_b64_e32 v[0:1], s[24:25]
	v_mad_u64_u32 v[2:3], s[0:1], v2, s19, v[0:1]
	v_mov_b32_e32 v89, v81
	v_lshl_add_u64 v[2:3], v[2:3], 0, v[88:89]
	v_lshlrev_b32_e32 v80, 1, v82
	v_lshl_add_u64 v[2:3], v[2:3], 0, v[80:81]
	s_mov_b64 s[2:3], 0x3000
	v_lshl_add_u64 v[4:5], v[2:3], 0, s[2:3]
	v_add_co_u32_e32 v2, vcc, 0x3000, v2
	v_or_b32_e32 v6, s6, v91
	s_nop 0
	v_addc_co_u32_e32 v3, vcc, 0, v3, vcc
	global_load_dwordx4 v[16:19], v[2:3], off
	global_load_dwordx4 v[20:23], v[4:5], off offset:32
	global_load_dwordx4 v[24:27], v[4:5], off offset:64
	global_load_dwordx4 v[28:31], v[4:5], off offset:96
	v_mad_i64_i32 v[2:3], s[0:1], v6, s19, v[0:1]
	v_add_co_u32_e32 v2, vcc, 0x3000, v2
	v_or_b32_e32 v6, 1, v6
	s_nop 0
	v_addc_co_u32_e32 v3, vcc, 0, v3, vcc
	global_load_dwordx4 v[2:5], v[2:3], off offset:1152
	v_mad_i64_i32 v[6:7], s[0:1], v6, s19, v[0:1]
	v_add_co_u32_e32 v6, vcc, 0x3000, v6
	s_or_b32 s6, s6, 4
	s_nop 0
	v_addc_co_u32_e32 v7, vcc, 0, v7, vcc
	v_or_b32_e32 v10, s6, v90
	global_load_dwordx4 v[6:9], v[6:7], off offset:1152
	v_mad_u64_u32 v[10:11], s[0:1], v10, s19, v[0:1]
	v_lshl_add_u64 v[10:11], v[10:11], 0, v[88:89]
	v_lshl_add_u64 v[10:11], v[10:11], 0, v[80:81]
	v_lshl_add_u64 v[12:13], v[10:11], 0, s[2:3]
	v_add_co_u32_e32 v10, vcc, 0x3000, v10
	v_or_b32_e32 v14, s6, v91
	s_nop 0
	v_addc_co_u32_e32 v11, vcc, 0, v11, vcc
	global_load_dwordx4 v[32:35], v[10:11], off
	global_load_dwordx4 v[36:39], v[12:13], off offset:32
	global_load_dwordx4 v[40:43], v[12:13], off offset:64
	global_load_dwordx4 v[44:47], v[12:13], off offset:96
	v_mad_i64_i32 v[10:11], s[0:1], v14, s19, v[0:1]
	v_add_co_u32_e32 v10, vcc, 0x3000, v10
	v_or_b32_e32 v14, 1, v14
	s_nop 0
	v_addc_co_u32_e32 v11, vcc, 0, v11, vcc
	global_load_dwordx4 v[10:13], v[10:11], off offset:1152
	v_mad_i64_i32 v[14:15], s[0:1], v14, s19, v[0:1]
	v_add_co_u32_e32 v14, vcc, 0x3000, v14
	v_readlane_b32 s0, v230, 46
	s_nop 0
	v_addc_co_u32_e32 v15, vcc, 0, v15, vcc
	global_load_dwordx4 v[48:51], v[14:15], off offset:1152
	s_add_i32 s0, s0, s31
	v_or_b32_e32 v195, s4, v91
	v_or_b32_e32 v197, s4, v92
	v_or_b32_e32 v196, 1, v195
	v_or_b32_e32 v198, 1, v197
	s_add_i32 s6, s31, 0x100
	v_mov_b32_e32 v199, v162
	v_mov_b32_e32 v200, v161
	s_mov_b32 s7, s82
	s_waitcnt vmcnt(7)
	v_lshlrev_b32_e32 v14, 16, v2
	v_and_b32_e32 v2, 0xffff0000, v2
	v_mul_f32_e32 v164, 0x3d3504f3, v2
	v_lshlrev_b32_e32 v2, 16, v3
	v_mul_f32_e32 v165, 0x3d3504f3, v2
	v_and_b32_e32 v2, 0xffff0000, v3
	v_mul_f32_e32 v166, 0x3d3504f3, v2
	v_lshlrev_b32_e32 v2, 16, v4
	v_mul_f32_e32 v167, 0x3d3504f3, v2
	v_and_b32_e32 v2, 0xffff0000, v4
	v_mul_f32_e32 v168, 0x3d3504f3, v2
	v_lshlrev_b32_e32 v2, 16, v5
	v_mul_f32_e32 v169, 0x3d3504f3, v2
	v_and_b32_e32 v2, 0xffff0000, v5
	v_mul_f32_e32 v170, 0x3d3504f3, v2
	s_waitcnt vmcnt(6)
	v_lshlrev_b32_e32 v2, 16, v6
	v_mul_f32_e32 v171, 0x3d3504f3, v2
	v_and_b32_e32 v2, 0xffff0000, v6
	v_mul_f32_e32 v172, 0x3d3504f3, v2
	v_lshlrev_b32_e32 v2, 16, v7
	v_mul_f32_e32 v173, 0x3d3504f3, v2
	v_and_b32_e32 v2, 0xffff0000, v7
	v_mul_f32_e32 v174, 0x3d3504f3, v2
	v_lshlrev_b32_e32 v2, 16, v8
	v_mul_f32_e32 v175, 0x3d3504f3, v2
	v_and_b32_e32 v2, 0xffff0000, v8
	v_mul_f32_e32 v176, 0x3d3504f3, v2
	v_lshlrev_b32_e32 v2, 16, v9
	v_mul_f32_e32 v177, 0x3d3504f3, v2
	v_and_b32_e32 v2, 0xffff0000, v9
	v_mul_f32_e32 v178, 0x3d3504f3, v2
	s_waitcnt vmcnt(1)
	v_lshlrev_b32_e32 v2, 16, v10
	v_mul_f32_e32 v179, 0x3d3504f3, v2
	v_and_b32_e32 v2, 0xffff0000, v10
	v_mul_f32_e32 v180, 0x3d3504f3, v2
	v_lshlrev_b32_e32 v2, 16, v11
	v_mul_f32_e32 v181, 0x3d3504f3, v2
	v_and_b32_e32 v2, 0xffff0000, v11
	v_mul_f32_e32 v182, 0x3d3504f3, v2
	v_lshlrev_b32_e32 v2, 16, v12
	v_mul_f32_e32 v183, 0x3d3504f3, v2
	v_and_b32_e32 v2, 0xffff0000, v12
	v_mul_f32_e32 v184, 0x3d3504f3, v2
	v_lshlrev_b32_e32 v2, 16, v13
	v_mul_f32_e32 v185, 0x3d3504f3, v2
	v_and_b32_e32 v2, 0xffff0000, v13
	v_mul_f32_e32 v186, 0x3d3504f3, v2
	s_waitcnt vmcnt(0)
	v_lshlrev_b32_e32 v2, 16, v48
	v_mul_f32_e32 v187, 0x3d3504f3, v2
	v_and_b32_e32 v2, 0xffff0000, v48
	v_mul_f32_e32 v188, 0x3d3504f3, v2
	v_lshlrev_b32_e32 v2, 16, v49
	v_mul_f32_e32 v189, 0x3d3504f3, v2
	v_and_b32_e32 v2, 0xffff0000, v49
	v_mul_f32_e32 v190, 0x3d3504f3, v2
	v_lshlrev_b32_e32 v2, 16, v50
	v_mul_f32_e32 v191, 0x3d3504f3, v2
	v_and_b32_e32 v2, 0xffff0000, v50
	v_mul_f32_e32 v192, 0x3d3504f3, v2
	v_lshlrev_b32_e32 v2, 16, v51
	v_mul_f32_e32 v193, 0x3d3504f3, v2
	v_and_b32_e32 v2, 0xffff0000, v51
	v_mul_f32_e32 v194, 0x3d3504f3, v2
	v_or_b32_e32 v2, s0, v85
	v_mad_u64_u32 v[0:1], s[0:1], v2, s19, v[0:1]
	v_lshl_add_u64 v[0:1], v[0:1], 0, v[80:81]
	v_lshl_add_u64 v[2:3], v[0:1], 0, s[10:11]
	v_add_co_u32_e32 v0, vcc, 0x3000, v0
	v_mul_f32_e32 v89, 0x3d3504f3, v14
	s_nop 0
	v_addc_co_u32_e32 v1, vcc, 0, v1, vcc
	global_load_dwordx4 v[60:63], v[0:1], off offset:1024
	global_load_dwordx4 v[56:59], v[2:3], off offset:32
	global_load_dwordx4 v[52:55], v[2:3], off offset:64
	global_load_dwordx4 v[48:51], v[2:3], off offset:96
	s_branch .LBB0_214
; #define MFMA32(a, b, c) __builtin_amdgcn_mfma_f32_32x32x16_bf16((a), (b), (c), 0, 0, 0)
; DI void index_unit(Frame& F, int b, int t0) {
;     ...
;         for (int kt = w; kt < nkt; kt += NWAVES) {
;             const int s = 32 * kt + r;
;             if (kt + NWAVES < nkt) { const bf16* kp = H0 + (size_t)(b * SEQ + s + 32 * NWAVES) * EVEN_LD + C_KI + 8 * hf;
; #pragma unroll
;                 for (int st = 0; st < 4; ++st) kn[st] = *(const bf16x8*)(kp + 16 * st); }
; #pragma unroll
;             for (int mt = 0; mt < 2; ++mt) {
;                 f32x16 x;
; #pragma unroll
;                 for (int i = 0; i < 16; ++i) x[i] = 0.f;
; #pragma unroll
;                 for (int st = 0; st < 4; ++st) x = MFMA32(qa[mt][st], kb[st], x);
;                 float s0v = 0.f, s1v = 0.f;
; #pragma unroll
;                 for (int i = 0; i < 8; ++i) { s0v += wv[mt][i] * fmaxf(x[i], 0.f); s1v += wv[mt][8 + i] * fmaxf(x[8 + i], 0.f); }
;                 const int tq0 = 4 * mt + 2 * hf;
;                 sc[tq0 * 4096 + s] = (s <= t0 + tq0) ? (s0v + 0.f) : -1e30f;
;                 sc[(tq0 + 1) * 4096 + s] = (s <= t0 + tq0 + 1) ? (s1v + 0.f) : -1e30f;
;             }
; #pragma unroll
;             for (int st = 0; st < 4; ++st) kb[st] = kn[st];
;         }
.Lidx_nopf:
	s_waitcnt vmcnt(0)
.LBB0_213:
	v_mfma_f32_32x32x16_bf16 v[0:15], v[16:19], v[60:63], 0
	v_cmp_le_i32_e32 vcc, v200, v195
	v_mfma_f32_32x32x16_bf16 v[0:15], v[20:23], v[56:59], v[0:15]
	v_mfma_f32_32x32x16_bf16 v[0:15], v[24:27], v[52:55], v[0:15]
	v_mfma_f32_32x32x16_bf16 v[0:15], v[28:31], v[48:51], v[0:15]
	s_nop 11
	v_max_f32_e32 v0, v0, v0
	v_max_f32_e32 v0, 0, v0
	v_max_f32_e32 v1, v1, v1
	v_fma_f32 v0, v89, v0, 0
	v_max_f32_e32 v8, v8, v8
	v_max_f32_e32 v1, 0, v1
	v_max_f32_e32 v8, 0, v8
	v_fmac_f32_e32 v0, v164, v1
	v_max_f32_e32 v1, v9, v9
	v_fma_f32 v8, v171, v8, 0
	v_max_f32_e32 v1, 0, v1
	v_fmac_f32_e32 v8, v172, v1
	v_max_f32_e32 v1, v2, v2
	v_max_f32_e32 v1, 0, v1
	v_fmac_f32_e32 v0, v165, v1
	v_max_f32_e32 v1, v10, v10
	v_max_f32_e32 v1, 0, v1
	v_fmac_f32_e32 v8, v173, v1
	v_max_f32_e32 v1, v3, v3
	v_max_f32_e32 v1, 0, v1
	v_fmac_f32_e32 v0, v166, v1
	v_max_f32_e32 v1, v11, v11
	v_max_f32_e32 v1, 0, v1
	v_fmac_f32_e32 v8, v174, v1
	v_max_f32_e32 v1, v4, v4
	v_max_f32_e32 v1, 0, v1
	v_fmac_f32_e32 v0, v167, v1
	v_max_f32_e32 v1, v12, v12
	v_max_f32_e32 v1, 0, v1
	v_fmac_f32_e32 v8, v175, v1
	v_max_f32_e32 v1, v5, v5
	v_max_f32_e32 v1, 0, v1
	v_fmac_f32_e32 v0, v168, v1
	v_max_f32_e32 v1, v13, v13
	v_max_f32_e32 v1, 0, v1
	v_fmac_f32_e32 v8, v176, v1
	v_max_f32_e32 v1, v6, v6
	v_max_f32_e32 v1, 0, v1
	v_fmac_f32_e32 v0, v169, v1
	v_max_f32_e32 v1, v14, v14
	v_max_f32_e32 v1, 0, v1
	v_fmac_f32_e32 v8, v177, v1
	v_max_f32_e32 v1, v7, v7
	v_max_f32_e32 v1, 0, v1
	v_fmac_f32_e32 v0, v170, v1
	v_max_f32_e32 v1, v15, v15
	v_max_f32_e32 v1, 0, v1
	v_add_f32_e32 v0, 0, v0
	v_fmac_f32_e32 v8, v178, v1
	v_cndmask_b32_e32 v0, v163, v0, vcc
	v_add_u32_e32 v1, 0xffff0000, v199
	ds_write_b32 v1, v0
	v_add_f32_e32 v0, 0, v8
	v_cmp_le_i32_e32 vcc, v200, v196
	v_add_u32_e32 v1, 0xffff4000, v199
	s_nop 0
	v_cndmask_b32_e32 v0, v163, v0, vcc
	ds_write_b32 v1, v0
	v_mfma_f32_32x32x16_bf16 v[0:15], v[32:35], v[60:63], 0
	v_cmp_le_i32_e32 vcc, v200, v197
	v_mfma_f32_32x32x16_bf16 v[0:15], v[36:39], v[56:59], v[0:15]
	v_mfma_f32_32x32x16_bf16 v[0:15], v[40:43], v[52:55], v[0:15]
	v_mfma_f32_32x32x16_bf16 v[0:15], v[44:47], v[48:51], v[0:15]
	s_nop 11
	v_max_f32_e32 v0, v0, v0
	v_max_f32_e32 v0, 0, v0
	v_max_f32_e32 v1, v1, v1
	v_fma_f32 v0, v179, v0, 0
	v_max_f32_e32 v8, v8, v8
	v_max_f32_e32 v1, 0, v1
	v_max_f32_e32 v8, 0, v8
	v_fmac_f32_e32 v0, v180, v1
	v_max_f32_e32 v1, v9, v9
	v_fma_f32 v8, v187, v8, 0
	v_max_f32_e32 v1, 0, v1
	v_fmac_f32_e32 v8, v188, v1
	v_max_f32_e32 v1, v2, v2
	v_max_f32_e32 v1, 0, v1
	v_fmac_f32_e32 v0, v181, v1
	v_max_f32_e32 v1, v10, v10
	v_max_f32_e32 v1, 0, v1
	v_fmac_f32_e32 v8, v189, v1
	v_max_f32_e32 v1, v3, v3
	v_max_f32_e32 v1, 0, v1
	v_fmac_f32_e32 v0, v182, v1
	v_max_f32_e32 v1, v11, v11
	v_max_f32_e32 v1, 0, v1
	v_fmac_f32_e32 v8, v190, v1
	v_max_f32_e32 v1, v4, v4
	v_max_f32_e32 v1, 0, v1
	v_fmac_f32_e32 v0, v183, v1
	v_max_f32_e32 v1, v12, v12
	v_max_f32_e32 v1, 0, v1
	v_fmac_f32_e32 v8, v191, v1
	v_max_f32_e32 v1, v5, v5
	v_max_f32_e32 v1, 0, v1
	v_fmac_f32_e32 v0, v184, v1
	v_max_f32_e32 v1, v13, v13
	v_max_f32_e32 v1, 0, v1
	v_fmac_f32_e32 v8, v192, v1
	v_max_f32_e32 v1, v6, v6
	v_max_f32_e32 v1, 0, v1
	v_fmac_f32_e32 v0, v185, v1
	v_max_f32_e32 v1, v14, v14
	v_max_f32_e32 v1, 0, v1
	v_fmac_f32_e32 v8, v193, v1
	v_max_f32_e32 v1, v7, v7
	v_max_f32_e32 v1, 0, v1
	v_fmac_f32_e32 v0, v186, v1
	v_max_f32_e32 v1, v15, v15
	v_max_f32_e32 v1, 0, v1
	v_fmac_f32_e32 v8, v194, v1
	v_add_f32_e32 v0, 0, v0
	v_cndmask_b32_e32 v0, v163, v0, vcc
	v_add_f32_e32 v1, 0, v8
	v_cmp_le_i32_e32 vcc, v200, v198
	v_add_u32_e32 v200, 0x100, v200
	s_nop 0
	v_cndmask_b32_e32 v1, v163, v1, vcc
	ds_write2st64_b32 v199, v0, v1 offset1:64
	v_add_u32_e32 v199, 0x400, v199
	s_waitcnt vmcnt(0)
	v_mov_b64_e32 v[60:61], v[68:69]
	v_mov_b64_e32 v[62:63], v[70:71]
	v_mov_b64_e32 v[56:57], v[64:65]
	v_mov_b64_e32 v[58:59], v[66:67]
	v_mov_b64_e32 v[52:53], v[72:73]
	v_mov_b64_e32 v[54:55], v[74:75]
	v_mov_b64_e32 v[48:49], v[76:77]
	v_mov_b64_e32 v[50:51], v[78:79]
	s_andn2_b64 vcc, exec, s[0:1]
	s_cbranch_vccz .LBB0_216
.LBB0_214:
	s_add_i32 s7, s7, 8
	s_cmp_ge_u32 s7, s5
	s_cselect_b64 s[0:1], -1, 0
	s_and_b64 vcc, exec, s[0:1]
	s_cbranch_vccnz .Lidx_nopf
	v_add_u32_e32 v2, s6, v200
	v_mov_b64_e32 v[0:1], s[24:25]
	v_mad_i64_i32 v[0:1], s[8:9], v2, s19, v[0:1]
	v_lshl_add_u64 v[0:1], v[0:1], 0, v[80:81]
	v_lshl_add_u64 v[2:3], v[0:1], 0, s[10:11]
	v_add_co_u32_e32 v0, vcc, 0x3000, v0
	s_nop 1
	v_addc_co_u32_e32 v1, vcc, 0, v1, vcc
	global_load_dwordx4 v[64:67], v[2:3], off offset:32
	global_load_dwordx4 v[72:75], v[2:3], off offset:64
	global_load_dwordx4 v[68:71], v[0:1], off offset:1024
	global_load_dwordx4 v[76:79], v[2:3], off offset:96
	s_waitcnt vmcnt(4)
	s_branch .LBB0_213

; #define LAS __attribute__((address_space(3)))
; template <int D, int STR>
; DI void load_q_frags(Frame& F, bf16x8* qf, const bf16* g0, size_t gstride, LAS unsigned char* buf) {
;     constexpr int CPR = D / 8, NCH = 256 * CPR / NTHR;
;     __syncthreads();
;     int tid_ = F.tid; asm volatile("" : "+v"(tid_));
; #pragma unroll
;     for (int hb = 0; hb < NCH; hb += 4) { u32x4 v[4];
; #pragma unroll
;       for (int k = 0; k < 4; ++k) { const int c = tid_ + (hb + k) * NTHR, r = c / CPR, q = c % CPR; v[k] = *(const u32x4*)(g0 + (size_t)r * gstride + q * 8); }
; #pragma unroll
;       for (int k = 0; k < 4; ++k) { const int c = tid_ + (hb + k) * NTHR, r = c / CPR, q = c % CPR; *(LAS u32x4*)(buf + r * STR + q * 16) = v[k]; } }
;     __syncthreads();
; DI void dsa_unit(Frame& F, int b, int h, int qb) {
;     const bf16* H0 = (const bf16*)(F.ws + WS_BIG); bf16* O = (bf16*)(F.ws + WS_XB);
;     const unsigned* mask = (const unsigned*)(F.ws + WS_MASK);
;     LAS unsigned char* Ks = F.lds + ATT_K_OFF; LAS unsigned char* Vs = F.lds + ATT_V_OFF;
;     LAS float* tb = (LAS float*)(F.lds + ATT_TB_OFF);
;     const int lane = F.lane, w = F.wave, tl = lane & 31, hf = lane >> 5;
;     const int t0 = 256 * qb, tw = t0 + 32 * w, t = tw + tl;
;     __syncthreads();
;     { const float* bd = (const float*)(F.ws + WS_BIASD) + h * 4096;
;       for (int i = F.tid; i < 4096; i += NTHR) tb[4095 - i] = bd[i]; }
;     bf16x8 qf[4];
;     load_q_frags<64, KSTR64>(F, qf, H0 + (size_t)(b * SEQ + t0) * EVEN_LD + C_QB + h * 64, EVEN_LD, Ks);
.LBB0_492:
	s_or_b64 exec, exec, s[12:13]
	s_lshl_b32 s29, s28, 8
	s_add_i32 s12, s29, s35
	s_add_i32 s56, s39, s29
	s_ashr_i32 s13, s12, 31
	s_mul_i32 s8, s12, 0x3600
	v_mov_b32_e32 v14, v146
	s_mul_hi_i32 s5, s12, 0x3600
	s_add_u32 s16, s24, s8
	s_waitcnt lgkmcnt(0)
	s_barrier
	s_addc_u32 s5, s25, s5
	v_add_u32_e32 v10, 0x400, v14
	s_lshl_b32 s8, s4, 6
	s_lshl_b32 s55, s4, 7
	v_ashrrev_i32_e32 v0, 31, v14
	v_ashrrev_i32_e32 v11, 31, v10
	s_add_u32 s16, s16, s55
	v_lshrrev_b32_e32 v0, 29, v0
	v_lshrrev_b32_e32 v11, 29, v11
	s_addc_u32 s5, s5, 0
	v_add_u32_e32 v0, v14, v0
	v_add_u32_e32 v11, v10, v11
	s_add_u32 s16, s16, 0x1800
	v_ashrrev_i32_e32 v16, 3, v0
	v_and_b32_e32 v0, -8, v0
	v_ashrrev_i32_e32 v20, 3, v11
	v_and_b32_e32 v11, -8, v11
	s_addc_u32 s17, s5, 0
	v_sub_u32_e32 v17, v14, v0
	v_sub_u32_e32 v21, v10, v11
	v_mov_b64_e32 v[8:9], s[16:17]
	v_lshlrev_b32_e32 v2, 3, v17
	v_lshlrev_b32_e32 v12, 3, v21
	v_mad_i64_i32 v[0:1], s[16:17], v16, s37, v[8:9]
	v_ashrrev_i32_e32 v3, 31, v2
	v_mad_i64_i32 v[10:11], s[16:17], v20, s37, v[8:9]
	v_ashrrev_i32_e32 v13, 31, v12
	v_lshl_add_u64 v[0:1], v[2:3], 1, v[0:1]
	v_add_u32_e32 v2, 0x200, v14
	v_lshl_add_u64 v[10:11], v[12:13], 1, v[10:11]
	v_add_u32_e32 v12, 0x600, v14
	v_ashrrev_i32_e32 v3, 31, v2
	v_ashrrev_i32_e32 v13, 31, v12
	v_lshrrev_b32_e32 v3, 29, v3
	v_lshrrev_b32_e32 v13, 29, v13
	v_add_u32_e32 v3, v2, v3
	v_add_u32_e32 v13, v12, v13
	v_ashrrev_i32_e32 v18, 3, v3
	v_and_b32_e32 v3, -8, v3
	v_ashrrev_i32_e32 v22, 3, v13
	v_and_b32_e32 v13, -8, v13
	v_sub_u32_e32 v19, v2, v3
	v_sub_u32_e32 v23, v12, v13
	v_lshlrev_b32_e32 v4, 3, v19
	v_lshlrev_b32_e32 v12, 3, v23
	v_mad_i64_i32 v[2:3], s[16:17], v18, s37, v[8:9]
	v_ashrrev_i32_e32 v5, 31, v4
	v_mad_i64_i32 v[8:9], s[16:17], v22, s37, v[8:9]
	v_ashrrev_i32_e32 v13, 31, v12
	v_lshl_add_u64 v[4:5], v[4:5], 1, v[2:3]
	v_lshl_add_u64 v[12:13], v[12:13], 1, v[8:9]
	global_load_dwordx4 v[0:3], v[0:1], off
	s_nop 0
	global_load_dwordx4 v[4:7], v[4:5], off
	s_nop 0
	global_load_dwordx4 v[8:11], v[10:11], off
	s_nop 0
	global_load_dwordx4 v[12:15], v[12:13], off
	s_add_i32 s16, s4, s36
	s_ashr_i32 s17, s16, 31
	s_lshl_b64 s[16:17], s[16:17], 2
	v_mul_lo_u32 v16, v16, s48
	v_lshlrev_b32_e32 v17, 4, v17
	s_add_u32 s16, s42, s16
	v_mov_b32_e32 v24, v144
	v_mul_lo_u32 v18, v18, s48
	v_mul_lo_u32 v20, v20, s48
	v_mul_lo_u32 v22, v22, s48
	v_add3_u32 v16, 0, v16, v17
	v_lshlrev_b32_e32 v17, 4, v19
	v_lshlrev_b32_e32 v19, 4, v21
	v_lshlrev_b32_e32 v21, 4, v23
	s_addc_u32 s17, s43, s17
	v_add3_u32 v17, 0, v18, v17
	v_add3_u32 v18, 0, v20, v19
	v_add3_u32 v19, 0, v22, v21
	s_mov_b32 s5, s9
	s_lshl_b64 s[4:5], s[4:5], 2
	s_add_u32 s4, s44, s4
	s_addc_u32 s5, s45, s5
	v_mov_b32_e32 v141, 0
	s_mov_b32 s58, 0
	s_mov_b32 s59, 0
	s_waitcnt vmcnt(3)
	ds_write_b128 v16, v[0:3]
	s_waitcnt vmcnt(2)
	ds_write_b128 v17, v[4:7]
	s_waitcnt vmcnt(1)
	ds_write_b128 v18, v[8:11]
	s_waitcnt vmcnt(0)
	ds_write_b128 v19, v[12:15]
	s_waitcnt lgkmcnt(0)
	s_barrier
; DI float swap_sum(float m) { auto rr = __builtin_amdgcn_permlane32_swap(__float_as_uint(m), __float_as_uint(m), false, false); return __uint_as_float(rr[0]) + __uint_as_float(rr[1]); }
; DI void dsa_unit(Frame& F, int b, int h, int qb) {
;     ...
;     float S;
;     { float qn = 0.f;
; #pragma unroll
;       for (int st = 0; st < 4; ++st)
; #pragma unroll
;           for (int q = 0; q < 8; ++q) { const float v = __uint_as_float(((unsigned)(unsigned short)qf[st][q]) << 16); qn += v * v; }
;       qn = swap_sum(qn);
;       const float k2 = __uint_as_float(((const unsigned*)(F.ws + WS_KMAX))[b * 16 + h]);
;       const float U = sqrtf(qn * k2) * C_D64 * 1.001f + ((const float*)(F.ws + WS_KMAX + 256))[h] + 0.01f;
;       S = fmaxf(U - 100.f, 0.f); }
;     const bool noshift = __all(S == 0.f);
;     float l = 0.f;
;     const unsigned* mrow = mask + (size_t)(b * SEQ + t) * 128;
;     const int jmax = (t0 + 255) >> 7;
;     RowRegs<64> RK, RV;
;     { const bf16* kg = H0 + (size_t)(b * SEQ) * EVEN_LD + C_KB + h * 64;
;       fetch_rows128<64>(RK, kg, EVEN_LD, F.tid); fetch_rows128<64>(RV, kg + (C_VB - C_KB), EVEN_LD, F.tid); }
;     u32x4 mwn = *(const u32x4*)(mrow);
;     for (int j = 0; j <= jmax; ++j) {
	global_load_dword v2, v107, s[16:17]
	v_and_or_b32 v0, v24, 31, s39
	v_ashrrev_i32_e32 v1, 1, v24
	v_mul_lo_u32 v0, v0, s48
	v_and_b32_e32 v1, -16, v1
	v_add3_u32 v0, 0, v0, v1
	ds_read_b128 v[64:67], v0
	ds_read_b128 v[68:71], v0 offset:32
	ds_read_b128 v[72:75], v0 offset:64
	ds_read_b128 v[76:79], v0 offset:96
	v_mov_b32_e32 v14, v107
	s_waitcnt lgkmcnt(3)
	v_and_b32_e32 v1, 0xffff0000, v64
	v_lshlrev_b32_e32 v0, 16, v64
	v_mul_f32_e32 v1, v1, v1
	v_fmac_f32_e32 v1, v0, v0
	v_lshlrev_b32_e32 v0, 16, v65
	v_fmac_f32_e32 v1, v0, v0
	v_and_b32_e32 v0, 0xffff0000, v65
	v_fmac_f32_e32 v1, v0, v0
	v_lshlrev_b32_e32 v0, 16, v66
	v_fmac_f32_e32 v1, v0, v0
	global_load_dword v0, v107, s[4:5]
	v_and_b32_e32 v3, 0xffff0000, v66
	v_fmac_f32_e32 v1, v3, v3
	v_lshlrev_b32_e32 v3, 16, v67
	v_fmac_f32_e32 v1, v3, v3
	v_and_b32_e32 v3, 0xffff0000, v67
	v_fmac_f32_e32 v1, v3, v3
	s_waitcnt lgkmcnt(2)
	v_lshlrev_b32_e32 v3, 16, v68
	v_fmac_f32_e32 v1, v3, v3
	v_and_b32_e32 v3, 0xffff0000, v68
	v_fmac_f32_e32 v1, v3, v3
	v_lshlrev_b32_e32 v3, 16, v69
	v_fmac_f32_e32 v1, v3, v3
	v_and_b32_e32 v3, 0xffff0000, v69
	v_fmac_f32_e32 v1, v3, v3
	v_lshlrev_b32_e32 v3, 16, v70
	v_fmac_f32_e32 v1, v3, v3
	v_and_b32_e32 v3, 0xffff0000, v70
	v_fmac_f32_e32 v1, v3, v3
	v_lshlrev_b32_e32 v3, 16, v71
	v_fmac_f32_e32 v1, v3, v3
	v_and_b32_e32 v3, 0xffff0000, v71
	v_fmac_f32_e32 v1, v3, v3
	s_waitcnt lgkmcnt(1)
	v_lshlrev_b32_e32 v3, 16, v72
	v_fmac_f32_e32 v1, v3, v3
	v_and_b32_e32 v3, 0xffff0000, v72
	v_fmac_f32_e32 v1, v3, v3
	v_lshlrev_b32_e32 v3, 16, v73
	v_fmac_f32_e32 v1, v3, v3
	v_and_b32_e32 v3, 0xffff0000, v73
	v_fmac_f32_e32 v1, v3, v3
	v_lshlrev_b32_e32 v3, 16, v74
	v_fmac_f32_e32 v1, v3, v3
	v_and_b32_e32 v3, 0xffff0000, v74
	v_fmac_f32_e32 v1, v3, v3
	v_lshlrev_b32_e32 v3, 16, v75
	v_fmac_f32_e32 v1, v3, v3
	v_and_b32_e32 v3, 0xffff0000, v75
	v_fmac_f32_e32 v1, v3, v3
	s_waitcnt lgkmcnt(0)
	v_lshlrev_b32_e32 v3, 16, v76
	v_fmac_f32_e32 v1, v3, v3
	v_and_b32_e32 v3, 0xffff0000, v76
	v_fmac_f32_e32 v1, v3, v3
	v_lshlrev_b32_e32 v3, 16, v77
	v_fmac_f32_e32 v1, v3, v3
	v_and_b32_e32 v3, 0xffff0000, v77
	v_fmac_f32_e32 v1, v3, v3
	v_lshlrev_b32_e32 v3, 16, v78
	v_fmac_f32_e32 v1, v3, v3
	v_and_b32_e32 v3, 0xffff0000, v78
	v_fmac_f32_e32 v1, v3, v3
	v_lshlrev_b32_e32 v3, 16, v79
	v_fmac_f32_e32 v1, v3, v3
	v_and_b32_e32 v3, 0xffff0000, v79
	v_fmac_f32_e32 v1, v3, v3
	v_mov_b32_e32 v3, v1
	s_nop 1
	v_permlane32_swap_b32_e32 v1, v3
	v_add_f32_e32 v1, v1, v3
	v_or_b32_e32 v3, s56, v159
	v_mov_b32_e32 v15, v107
	v_mov_b32_e32 v8, v107
	s_waitcnt vmcnt(1)
	v_mul_f32_e32 v1, v2, v1
	v_mul_f32_e32 v2, 0x4f800000, v1
	v_cmp_gt_f32_e32 vcc, s51, v1
	v_mov_b32_e32 v9, v107
	v_mov_b32_e32 v10, v107
	v_cndmask_b32_e32 v1, v1, v2, vcc
	v_sqrt_f32_e32 v2, v1
	v_mov_b32_e32 v11, v107
	v_mov_b32_e32 v12, v107
	v_mov_b32_e32 v13, v107
	v_add_u32_e32 v4, -1, v2
	v_fma_f32 v5, -v4, v2, v1
	v_cmp_ge_f32_e64 s[4:5], 0, v5
	v_add_u32_e32 v5, 1, v2
	s_nop 0
	v_cndmask_b32_e64 v4, v2, v4, s[4:5]
	v_fma_f32 v2, -v5, v2, v1
	v_cmp_lt_f32_e64 s[4:5], 0, v2
	s_nop 1
	v_cndmask_b32_e64 v2, v4, v5, s[4:5]
	v_mul_f32_e32 v4, 0x37800000, v2
	v_cndmask_b32_e32 v2, v2, v4, vcc
	v_cmp_class_f32_e32 vcc, v1, v134
	s_nop 1
	v_cndmask_b32_e32 v1, v2, v1, vcc
	v_mul_f32_e32 v1, 0x3e38aa3b, v1
	s_waitcnt vmcnt(0)
	v_fmac_f32_e32 v0, 0x3f8020c5, v1
	v_add_f32_e32 v0, 0x3c23d70a, v0
	v_add_f32_e32 v0, 0xc2c80000, v0
	v_max_f32_e32 v138, 0, v0
	v_cmp_eq_f32_e32 vcc, 0, v138
	s_cmp_lg_u64 vcc, exec
	s_cselect_b64 s[16:17], -1, 0
	s_lshl_b32 s54, s28, 1
	s_add_u32 s4, s46, s55
	v_add_u32_e32 v0, s35, v3
	s_addc_u32 s5, s47, 0
	v_ashrrev_i32_e32 v1, 31, v0
	v_lshl_add_u64 v[6:7], s[4:5], 0, v[108:109]
	v_lshlrev_b64 v[0:1], 9, v[0:1]
	v_lshl_add_u64 v[4:5], s[4:5], 0, v[104:105]
	v_lshl_add_u64 v[6:7], v[6:7], 0, v[106:107]
	v_lshl_add_u64 v[2:3], s[6:7], 0, v[0:1]
	v_lshl_add_u64 v[4:5], v[4:5], 0, v[106:107]
	global_load_dwordx4 v[88:91], v[6:7], off
	global_load_dwordx4 v[84:87], v[4:5], off offset:2048
	global_load_dwordx4 v[80:83], v[4:5], off
	global_load_dwordx4 v[100:103], v[2:3], off
	global_load_dwordx4 v[92:95], v[6:7], off offset:2048
	v_lshl_add_u64 v[112:113], s[10:11], 0, v[0:1]
	v_add_lshl_u32 v0, v130, s29, 2
	s_lshl_b32 s57, s28, 10
	v_sub_u32_e32 v139, v119, v0
	v_mov_b32_e32 v0, v107
	v_mov_b32_e32 v1, v107
	v_mov_b32_e32 v2, v107
	v_mov_b32_e32 v3, v107
	v_mov_b32_e32 v4, v107
	v_mov_b32_e32 v5, v107
	v_mov_b32_e32 v6, v107
	v_mov_b32_e32 v7, v107
	v_mov_b64_e32 v[30:31], v[14:15]
	s_mov_b32 s55, 0
	s_or_b32 s56, s56, 31
	s_addk_i32 s57, 0x400
	v_mov_b64_e32 v[28:29], v[12:13]
	v_mov_b64_e32 v[26:27], v[10:11]
	v_mov_b64_e32 v[24:25], v[8:9]
	v_mov_b64_e32 v[22:23], v[6:7]
	v_mov_b64_e32 v[20:21], v[4:5]
	v_mov_b64_e32 v[18:19], v[2:3]
	v_mov_b64_e32 v[16:17], v[0:1]
	s_waitcnt vmcnt(1)
	v_mov_b64_e32 v[96:97], v[100:101]
	v_mov_b64_e32 v[98:99], v[102:103]
	s_add_i32 s98, s49, s58
	s_mul_hi_i32 s99, s98, 0x3600
	s_mulk_i32 s98, 0x3600
	s_add_u32 s98, s24, s98
	s_addc_u32 s99, s25, s99
	s_lshl_b32 s100, s8, 1
	s_add_u32 s98, s98, s100
	s_addc_u32 s99, s99, 0
	s_add_u32 s98, s98, 0x2000
	s_addc_u32 s99, s99, 0
	v_lshl_add_u64 v[32:33], s[98:99], 0, v[104:105]
	v_lshl_add_u64 v[32:33], v[32:33], 0, v[106:107]
	v_lshl_add_u64 v[34:35], s[98:99], 0, v[108:109]
	v_lshl_add_u64 v[34:35], v[34:35], 0, v[106:107]
	global_load_dwordx4 v[232:235], v[32:33], off
	global_load_dwordx4 v[236:239], v[32:33], off offset:2048
	global_load_dwordx4 v[240:243], v[34:35], off
	global_load_dwordx4 v[244:247], v[34:35], off offset:2048
	global_load_dwordx4 v[248:251], v[112:113], off
.LBB0_493:
	s_barrier
	s_bitcmp1_b32 s59, 0
	s_cbranch_scc1 .Ldsa_top_b
	s_cmp_gt_u32 s59, s54
	s_cbranch_scc1 .Ldsa_wa0
	s_waitcnt vmcnt(5)
	s_branch .Ldsa_wa1

; DI void dsa_unit(Frame& F, int b, int h, int qb) {
;     ...
;     for (int j = 0; j <= jmax; ++j) {
;         __syncthreads();
;         put_rows128<64, KSTR64>(Ks, RK, F.tid); put_rows128<64, VSTR64>(Vs, RV, F.tid);
;         const u32x4 mw4 = mwn;
;         __syncthreads();
;         if (j < jmax) { const bf16* kg = H0 + (size_t)(b * SEQ + 128 * (j + 1)) * EVEN_LD + C_KB + h * 64;
;             fetch_rows128<64>(RK, kg, EVEN_LD, F.tid); fetch_rows128<64>(RV, kg + (C_VB - C_KB), EVEN_LD, F.tid);
;             mwn = *(const u32x4*)(mrow + 4 * (j + 1)); }
.Ldsa_wa1:
	ds_write_b128 v135, v[80:83]
	ds_write_b128 v136, v[88:91]
	ds_write_b128 v135, v[84:87] offset:36864
	ds_write_b128 v136, v[92:95] offset:36864
	v_mov_b64_e32 v[100:101], v[96:97]
	v_mov_b64_e32 v[102:103], v[98:99]
	s_waitcnt lgkmcnt(0)
	s_barrier
	s_cmp_ge_u32 s59, s54
	s_cbranch_scc1 .LBB0_495
	s_add_i32 s98, s49, s58
	s_addk_i32 s98, 0x80
	s_mul_hi_i32 s99, s98, 0x3600
	s_mulk_i32 s98, 0x3600
	s_add_u32 s98, s24, s98
	s_addc_u32 s99, s25, s99
	s_lshl_b32 s100, s8, 1
	s_add_u32 s98, s98, s100
	s_addc_u32 s99, s99, 0
	s_add_u32 s98, s98, 0x2000
	s_addc_u32 s99, s99, 0
	v_lshl_add_u64 v[32:33], s[98:99], 0, v[104:105]
	v_lshl_add_u64 v[32:33], v[32:33], 0, v[106:107]
	v_lshl_add_u64 v[34:35], s[98:99], 0, v[108:109]
	v_lshl_add_u64 v[34:35], v[34:35], 0, v[106:107]
	global_load_dwordx4 v[80:83], v[32:33], off
	global_load_dwordx4 v[84:87], v[32:33], off offset:2048
	global_load_dwordx4 v[88:91], v[34:35], off
	global_load_dwordx4 v[92:95], v[34:35], off offset:2048
	global_load_dwordx4 v[96:99], v[112:113], off offset:16
	s_branch .LBB0_495
.Ldsa_top_b:
	s_cmp_gt_u32 s59, s54
	s_cbranch_scc1 .Ldsa_wb0
	s_waitcnt vmcnt(5)
	s_branch .Ldsa_wb1

; #define LAS __attribute__((address_space(3)))
; DI void dsa_unit(Frame& F, int b, int h, int qb) {
;     ...
;     for (int j = 0; j <= jmax; ++j) {
;         __syncthreads();
;         put_rows128<64, KSTR64>(Ks, RK, F.tid); put_rows128<64, VSTR64>(Vs, RV, F.tid);
;         const u32x4 mw4 = mwn;
;         __syncthreads();
;         if (j < jmax) { const bf16* kg = H0 + (size_t)(b * SEQ + 128 * (j + 1)) * EVEN_LD + C_KB + h * 64;
;             fetch_rows128<64>(RK, kg, EVEN_LD, F.tid); fetch_rows128<64>(RV, kg + (C_VB - C_KB), EVEN_LD, F.tid);
;             mwn = *(const u32x4*)(mrow + 4 * (j + 1)); }
; #pragma unroll
;         for (int kt = 0; kt < 4; ++kt) {
;             const int s0 = 128 * j + 32 * kt;
;             if (s0 > tw + 31) continue;
;             const unsigned mws = mw4[kt] >> (4 * hf);
;             f32x16 x = st_tile<64, KSTR64>(Ks, 32 * kt, qf, tl, hf);
;             const LAS float* tp = tb + (4095 - (t - s0 - 4 * hf));
;             if (noshift) {
.Ldsa_wb1:
	ds_write_b128 v135, v[232:235]
	ds_write_b128 v136, v[240:243]
	ds_write_b128 v135, v[236:239] offset:36864
	ds_write_b128 v136, v[244:247] offset:36864
	v_mov_b64_e32 v[100:101], v[248:249]
	v_mov_b64_e32 v[102:103], v[250:251]
	s_waitcnt lgkmcnt(0)
	s_barrier
	s_cmp_ge_u32 s59, s54
	s_cbranch_scc1 .LBB0_495
	s_add_i32 s98, s49, s58
	s_addk_i32 s98, 0x80
	s_mul_hi_i32 s99, s98, 0x3600
	s_mulk_i32 s98, 0x3600
	s_add_u32 s98, s24, s98
	s_addc_u32 s99, s25, s99
	s_lshl_b32 s100, s8, 1
	s_add_u32 s98, s98, s100
	s_addc_u32 s99, s99, 0
	s_add_u32 s98, s98, 0x2000
	s_addc_u32 s99, s99, 0
	v_lshl_add_u64 v[32:33], s[98:99], 0, v[104:105]
	v_lshl_add_u64 v[32:33], v[32:33], 0, v[106:107]
	v_lshl_add_u64 v[34:35], s[98:99], 0, v[108:109]
	v_lshl_add_u64 v[34:35], v[34:35], 0, v[106:107]
	global_load_dwordx4 v[232:235], v[32:33], off
	global_load_dwordx4 v[236:239], v[32:33], off offset:2048
	global_load_dwordx4 v[240:243], v[34:35], off
	global_load_dwordx4 v[244:247], v[34:35], off offset:2048
	global_load_dwordx4 v[248:251], v[112:113], off offset:16
.LBB0_495:
	s_add_i32 s98, s58, 0x60
	s_cmp_gt_u32 s98, s56
	s_cbranch_scc1 .Ldsa_slow
	s_cmp_eq_u64 s[16:17], 0
	s_cbranch_scc1 .Ldsa_fast

; #define LAS __attribute__((address_space(3)))
; template <int D, int STR>
; DI f32x16 st_tile(LAS const unsigned char* Ks, int krow0, const bf16x8* qf, int tl, int hf) {
;     f32x16 x;
; #pragma unroll
;     for (int i = 0; i < 16; ++i) x[i] = 0.f;
;     LAS const unsigned char* kp = Ks + (krow0 + tl) * STR + hf * 16;
; #pragma unroll
;     for (int st = 0; st < D / 16; ++st) { const bf16x8 kf = *(LAS const bf16x8*)(kp + st * 32); x = MFMA32(kf, qf[st], x); }
;     return x;
; }
; template <int D, int STR>
; DI void pv_tile(f32x16* acc, LAS const unsigned char* Vs, int vrow0, bf16x8 p0, bf16x8 p1, int lane) {
;     const int hf = lane >> 5, q = (lane & 15) >> 2, p = lane & 3, blk = (lane >> 4) & 1;
;     LAS const char* vb = (LAS const char*)Vs + (vrow0 + 4 * hf + q) * STR + blk * 32 + p * 8;
; #pragma unroll
;     for (int eb = 0; eb < D / 32; ++eb) {
;         const s16x4 l0 = vtr(vb + eb * 64), h0 = vtr(vb + 8 * STR + eb * 64);
;         const s16x4 l1 = vtr(vb + 16 * STR + eb * 64), h1 = vtr(vb + 24 * STR + eb * 64);
; DI void dsa_unit(Frame& F, int b, int h, int qb) {
;     ...
; #pragma unroll
;         for (int kt = 0; kt < 4; ++kt) {
;             const int s0 = 128 * j + 32 * kt;
;             if (s0 > tw + 31) continue;
;             const unsigned mws = mw4[kt] >> (4 * hf);
;             f32x16 x = st_tile<64, KSTR64>(Ks, 32 * kt, qf, tl, hf);
;             const LAS float* tp = tb + (4095 - (t - s0 - 4 * hf));
;             if (noshift) {
; #pragma unroll
;                 for (int i = 0; i < 16; ++i) {
;                     const int ci = (i & 3) + 8 * (i >> 2);
;                     const unsigned mm = (unsigned)__builtin_amdgcn_sbfe((int)mws, ci, 1);
;                     x[i] = ex2(bfi_f(mm, x[i] * C_D64 + tp[ci], -INFINITY));
;                     l += x[i];
;                 }
;             } else {
; #pragma unroll
;                 for (int i = 0; i < 16; ++i) {
;                     const int ci = (i & 3) + 8 * (i >> 2);
;                     const unsigned mm = (unsigned)__builtin_amdgcn_sbfe((int)mws, ci, 1);
;                     x[i] = ex2(bfi_f(mm, x[i] * C_D64 + tp[ci], -INFINITY) - S);
;                     l += x[i];
;                 }
;             }
;             const bf16x8 p0 = pack8(x, 0), p1 = pack8(x, 1);
;             pv_tile<64, VSTR64>(acc, Vs, 32 * kt, p0, p1, lane);
.LBB0_519:
	s_add_i32 s59, s59, 1
	s_addk_i32 s58, 0x80
	s_addk_i32 s55, 0x200
	s_cmp_lg_u32 s57, s55
	v_lshl_add_u64 v[112:113], v[112:113], 0, 16
	s_cbranch_scc0 .LBB0_483
	s_branch .LBB0_493
.Ldsa_fast:
	s_add_i32 s98, s55, 0x15ffc
	v_add_u32_e32 v228, v120, v121
	v_add_u32_e32 v227, s98, v139
	ds_read_b128 v[48:51], v137 offset:0
	ds_read_b128 v[52:55], v137 offset:32
	ds_read_b128 v[56:59], v137 offset:64
	ds_read_b128 v[148:151], v137 offset:96
	v_lshrrev_b32_e32 v226, v160, v100
	ds_read2_b32 v[206:207], v227 offset0:0 offset1:1
	ds_read2_b32 v[208:209], v227 offset0:2 offset1:3
	ds_read2_b32 v[210:211], v227 offset0:8 offset1:9
	ds_read2_b32 v[212:213], v227 offset0:10 offset1:11
	ds_read2_b32 v[214:215], v227 offset0:16 offset1:17
	ds_read2_b32 v[216:217], v227 offset0:18 offset1:19
	ds_read2_b32 v[218:219], v227 offset0:24 offset1:25
	ds_read2_b32 v[220:221], v227 offset0:26 offset1:27
	s_waitcnt lgkmcnt(11)
	v_mfma_f32_32x32x16_bf16 v[32:47], v[48:51], v[64:67], 0
	s_waitcnt lgkmcnt(10)
	v_mfma_f32_32x32x16_bf16 v[32:47], v[52:55], v[68:71], v[32:47]
	s_waitcnt lgkmcnt(9)
	v_mfma_f32_32x32x16_bf16 v[32:47], v[56:59], v[72:75], v[32:47]
	s_waitcnt lgkmcnt(8)
	v_mfma_f32_32x32x16_bf16 v[32:47], v[148:151], v[76:79], v[32:47]
	ds_read_b128 v[48:51], v137 offset:4608
	ds_read_b128 v[52:55], v137 offset:4640
	ds_read_b128 v[56:59], v137 offset:4672
	ds_read_b128 v[148:151], v137 offset:4704
	ds_read_b64_tr_b16 v[222:223], v228 offset:36864
	ds_read_b64_tr_b16 v[224:225], v228 offset:38016
	ds_read_b64_tr_b16 v[252:253], v228 offset:36928
	ds_read_b64_tr_b16 v[254:255], v228 offset:38080
	ds_read_b64_tr_b16 v[194:195], v228 offset:39168
	ds_read_b64_tr_b16 v[196:197], v228 offset:40320
	ds_read_b64_tr_b16 v[170:171], v228 offset:39232
	ds_read_b64_tr_b16 v[172:173], v228 offset:40384
	s_nop 3
	s_waitcnt lgkmcnt(12)
	v_bfe_i32 v60, v226, 0, 1
	v_fmac_f32_e32 v206, 0x3e38aa3b, v32
	v_bitop3_b32 v206, v206, s52, v60 bitop3:0xe4
	v_exp_f32_e32 v206, v206
	s_waitcnt lgkmcnt(11)
	v_mfma_f32_32x32x16_bf16 v[178:193], v[48:51], v[64:67], 0
	v_bfe_i32 v61, v226, 1, 1
	v_fmac_f32_e32 v207, 0x3e38aa3b, v33
	v_bitop3_b32 v207, v207, s52, v61 bitop3:0xe4
	v_exp_f32_e32 v207, v207
	v_add_f32_e32 v141, v141, v206
	v_bfe_i32 v60, v226, 2, 1
	v_fmac_f32_e32 v208, 0x3e38aa3b, v34
	v_bitop3_b32 v208, v208, s52, v60 bitop3:0xe4
	v_exp_f32_e32 v208, v208
	v_add_f32_e32 v141, v141, v207
	s_waitcnt lgkmcnt(10)
	v_mfma_f32_32x32x16_bf16 v[178:193], v[52:55], v[68:71], v[178:193]
	v_cvt_pk_bf16_f32 v152, v206, v207
	v_bfe_i32 v61, v226, 3, 1
	v_fmac_f32_e32 v209, 0x3e38aa3b, v35
	v_bitop3_b32 v209, v209, s52, v61 bitop3:0xe4
	v_exp_f32_e32 v209, v209
	v_add_f32_e32 v141, v141, v208
	v_bfe_i32 v60, v226, 8, 1
	v_fmac_f32_e32 v210, 0x3e38aa3b, v36
	v_bitop3_b32 v210, v210, s52, v60 bitop3:0xe4
	v_exp_f32_e32 v210, v210
	s_waitcnt lgkmcnt(9)
	v_mfma_f32_32x32x16_bf16 v[178:193], v[56:59], v[72:75], v[178:193]
	v_add_f32_e32 v141, v141, v209
	v_cvt_pk_bf16_f32 v153, v208, v209
	v_bfe_i32 v61, v226, 9, 1
	v_fmac_f32_e32 v211, 0x3e38aa3b, v37
	v_bitop3_b32 v211, v211, s52, v61 bitop3:0xe4
	v_exp_f32_e32 v211, v211
	v_add_f32_e32 v141, v141, v210
	v_bfe_i32 v60, v226, 10, 1
	v_fmac_f32_e32 v212, 0x3e38aa3b, v38
	v_bitop3_b32 v212, v212, s52, v60 bitop3:0xe4
	s_waitcnt lgkmcnt(8)
	v_mfma_f32_32x32x16_bf16 v[178:193], v[148:151], v[76:79], v[178:193]
	v_exp_f32_e32 v212, v212
	v_add_f32_e32 v141, v141, v211
	v_cvt_pk_bf16_f32 v154, v210, v211
	v_bfe_i32 v61, v226, 11, 1
	v_fmac_f32_e32 v213, 0x3e38aa3b, v39
	v_bitop3_b32 v213, v213, s52, v61 bitop3:0xe4
	v_exp_f32_e32 v213, v213
	v_add_f32_e32 v141, v141, v212
	v_add_f32_e32 v141, v141, v213
	v_cvt_pk_bf16_f32 v155, v212, v213
	v_bfe_i32 v60, v226, 16, 1
	v_fmac_f32_e32 v214, 0x3e38aa3b, v40
	v_bitop3_b32 v214, v214, s52, v60 bitop3:0xe4
	s_waitcnt lgkmcnt(6)
	v_mfma_f32_32x32x16_bf16 v[16:31], v[222:225], v[152:155], v[16:31]
	v_exp_f32_e32 v214, v214
	v_bfe_i32 v61, v226, 17, 1
	v_fmac_f32_e32 v215, 0x3e38aa3b, v41
	v_bitop3_b32 v215, v215, s52, v61 bitop3:0xe4
	v_exp_f32_e32 v215, v215
	v_add_f32_e32 v141, v141, v214
	v_bfe_i32 v60, v226, 18, 1
	v_fmac_f32_e32 v216, 0x3e38aa3b, v42
	v_bitop3_b32 v216, v216, s52, v60 bitop3:0xe4
	v_exp_f32_e32 v216, v216
	v_add_f32_e32 v141, v141, v215
	v_cvt_pk_bf16_f32 v198, v214, v215
	v_bfe_i32 v61, v226, 19, 1
	s_waitcnt lgkmcnt(4)
	v_mfma_f32_32x32x16_bf16 v[0:15], v[252:255], v[152:155], v[0:15]
	ds_read_b128 v[48:51], v137 offset:9216
	ds_read_b128 v[52:55], v137 offset:9248
	ds_read_b128 v[56:59], v137 offset:9280
	ds_read_b128 v[148:151], v137 offset:9312
	ds_read2_b32 v[206:207], v227 offset0:32 offset1:33
	ds_read2_b32 v[208:209], v227 offset0:34 offset1:35
	ds_read2_b32 v[210:211], v227 offset0:40 offset1:41
	ds_read2_b32 v[212:213], v227 offset0:42 offset1:43
	v_fmac_f32_e32 v217, 0x3e38aa3b, v43
	v_bitop3_b32 v217, v217, s52, v61 bitop3:0xe4
	v_exp_f32_e32 v217, v217
	v_add_f32_e32 v141, v141, v216
	v_bfe_i32 v60, v226, 24, 1
	v_fmac_f32_e32 v218, 0x3e38aa3b, v44
	v_bitop3_b32 v218, v218, s52, v60 bitop3:0xe4
	v_exp_f32_e32 v218, v218
	v_add_f32_e32 v141, v141, v217
	v_cvt_pk_bf16_f32 v199, v216, v217
	v_bfe_i32 v61, v226, 25, 1
	v_fmac_f32_e32 v219, 0x3e38aa3b, v45
	v_bitop3_b32 v219, v219, s52, v61 bitop3:0xe4
	v_exp_f32_e32 v219, v219
	v_add_f32_e32 v141, v141, v218
	v_bfe_i32 v60, v226, 26, 1
	v_fmac_f32_e32 v220, 0x3e38aa3b, v46
	v_bitop3_b32 v220, v220, s52, v60 bitop3:0xe4
	v_exp_f32_e32 v220, v220
	v_add_f32_e32 v141, v141, v219
	v_cvt_pk_bf16_f32 v200, v218, v219
	v_bfe_i32 v61, v226, 27, 1
	v_fmac_f32_e32 v221, 0x3e38aa3b, v47
	v_bitop3_b32 v221, v221, s52, v61 bitop3:0xe4
	v_exp_f32_e32 v221, v221
	v_add_f32_e32 v141, v141, v220
	v_add_f32_e32 v141, v141, v221
	v_cvt_pk_bf16_f32 v201, v220, v221
	s_nop 1
	s_waitcnt lgkmcnt(10)
; #define LAS __attribute__((address_space(3)))
; #define MFMA32(a, b, c) __builtin_amdgcn_mfma_f32_32x32x16_bf16((a), (b), (c), 0, 0, 0)
; DI float ex2(float x) { return __builtin_amdgcn_exp2f(x); }
; template <int D, int STR>
; DI void pv_tile(f32x16* acc, LAS const unsigned char* Vs, int vrow0, bf16x8 p0, bf16x8 p1, int lane) {
;     const int hf = lane >> 5, q = (lane & 15) >> 2, p = lane & 3, blk = (lane >> 4) & 1;
;     LAS const char* vb = (LAS const char*)Vs + (vrow0 + 4 * hf + q) * STR + blk * 32 + p * 8;
; #pragma unroll
;     for (int eb = 0; eb < D / 32; ++eb) {
;         const s16x4 l0 = vtr(vb + eb * 64), h0 = vtr(vb + 8 * STR + eb * 64);
;         const s16x4 l1 = vtr(vb + 16 * STR + eb * 64), h1 = vtr(vb + 24 * STR + eb * 64);
;         const bf16x8 v0 = __builtin_shufflevector(l0, h0, 0, 1, 2, 3, 4, 5, 6, 7), v1 = __builtin_shufflevector(l1, h1, 0, 1, 2, 3, 4, 5, 6, 7);
;         acc[eb] = MFMA32(v0, p0, acc[eb]); acc[eb] = MFMA32(v1, p1, acc[eb]);
;     }
; }
; DI void dsa_unit(Frame& F, int b, int h, int qb) {
;     ...
;         for (int kt = 0; kt < 4; ++kt) {
;             const int s0 = 128 * j + 32 * kt;
;             if (s0 > tw + 31) continue;
;             const unsigned mws = mw4[kt] >> (4 * hf);
;             f32x16 x = st_tile<64, KSTR64>(Ks, 32 * kt, qf, tl, hf);
;             const LAS float* tp = tb + (4095 - (t - s0 - 4 * hf));
;             if (noshift) {
; #pragma unroll
;                 for (int i = 0; i < 16; ++i) {
;                     const int ci = (i & 3) + 8 * (i >> 2);
;                     const unsigned mm = (unsigned)__builtin_amdgcn_sbfe((int)mws, ci, 1);
;                     x[i] = ex2(bfi_f(mm, x[i] * C_D64 + tp[ci], -INFINITY));
;                     l += x[i];
;                 }
;             } else {
; #pragma unroll
;                 for (int i = 0; i < 16; ++i) {
;                     const int ci = (i & 3) + 8 * (i >> 2);
;                     const unsigned mm = (unsigned)__builtin_amdgcn_sbfe((int)mws, ci, 1);
;                     x[i] = ex2(bfi_f(mm, x[i] * C_D64 + tp[ci], -INFINITY) - S);
;                     l += x[i];
;                 }
;             }
;             const bf16x8 p0 = pack8(x, 0), p1 = pack8(x, 1);
;             pv_tile<64, VSTR64>(acc, Vs, 32 * kt, p0, p1, lane);
	v_mfma_f32_32x32x16_bf16 v[16:31], v[194:197], v[198:201], v[16:31]
	s_waitcnt lgkmcnt(8)
	v_mfma_f32_32x32x16_bf16 v[0:15], v[170:173], v[198:201], v[0:15]
	ds_read_b64_tr_b16 v[222:223], v228 offset:41472
	ds_read_b64_tr_b16 v[224:225], v228 offset:42624
	ds_read_b64_tr_b16 v[252:253], v228 offset:41536
	ds_read_b64_tr_b16 v[254:255], v228 offset:42688
	ds_read_b64_tr_b16 v[194:195], v228 offset:43776
	ds_read_b64_tr_b16 v[196:197], v228 offset:44928
	ds_read_b64_tr_b16 v[170:171], v228 offset:43840
	ds_read_b64_tr_b16 v[172:173], v228 offset:44992
	ds_read2_b32 v[214:215], v227 offset0:48 offset1:49
	ds_read2_b32 v[216:217], v227 offset0:50 offset1:51
	ds_read2_b32 v[218:219], v227 offset0:56 offset1:57
	ds_read2_b32 v[220:221], v227 offset0:58 offset1:59
	v_lshrrev_b32_e32 v226, v160, v101
	s_waitcnt lgkmcnt(12)
	v_bfe_i32 v60, v226, 0, 1
	v_fmac_f32_e32 v206, 0x3e38aa3b, v178
	v_bitop3_b32 v206, v206, s52, v60 bitop3:0xe4
	v_exp_f32_e32 v206, v206
	v_mfma_f32_32x32x16_bf16 v[32:47], v[48:51], v[64:67], 0
	v_bfe_i32 v61, v226, 1, 1
	v_fmac_f32_e32 v207, 0x3e38aa3b, v179
	v_bitop3_b32 v207, v207, s52, v61 bitop3:0xe4
	v_exp_f32_e32 v207, v207
	v_add_f32_e32 v141, v141, v206
	v_bfe_i32 v60, v226, 2, 1
	v_fmac_f32_e32 v208, 0x3e38aa3b, v180
	v_bitop3_b32 v208, v208, s52, v60 bitop3:0xe4
	v_exp_f32_e32 v208, v208
	v_add_f32_e32 v141, v141, v207
	v_mfma_f32_32x32x16_bf16 v[32:47], v[52:55], v[68:71], v[32:47]
	v_cvt_pk_bf16_f32 v152, v206, v207
	v_bfe_i32 v61, v226, 3, 1
	v_fmac_f32_e32 v209, 0x3e38aa3b, v181
	v_bitop3_b32 v209, v209, s52, v61 bitop3:0xe4
	v_exp_f32_e32 v209, v209
	v_add_f32_e32 v141, v141, v208
	v_bfe_i32 v60, v226, 8, 1
	v_fmac_f32_e32 v210, 0x3e38aa3b, v182
	v_bitop3_b32 v210, v210, s52, v60 bitop3:0xe4
	v_exp_f32_e32 v210, v210
	v_mfma_f32_32x32x16_bf16 v[32:47], v[56:59], v[72:75], v[32:47]
	v_add_f32_e32 v141, v141, v209
	v_cvt_pk_bf16_f32 v153, v208, v209
	v_bfe_i32 v61, v226, 9, 1
	v_fmac_f32_e32 v211, 0x3e38aa3b, v183
	v_bitop3_b32 v211, v211, s52, v61 bitop3:0xe4
	v_exp_f32_e32 v211, v211
	v_add_f32_e32 v141, v141, v210
	v_bfe_i32 v60, v226, 10, 1
	v_fmac_f32_e32 v212, 0x3e38aa3b, v184
	v_bitop3_b32 v212, v212, s52, v60 bitop3:0xe4
	v_mfma_f32_32x32x16_bf16 v[32:47], v[148:151], v[76:79], v[32:47]
	v_exp_f32_e32 v212, v212
	v_add_f32_e32 v141, v141, v211
	v_cvt_pk_bf16_f32 v154, v210, v211
	v_bfe_i32 v61, v226, 11, 1
	v_fmac_f32_e32 v213, 0x3e38aa3b, v185
	v_bitop3_b32 v213, v213, s52, v61 bitop3:0xe4
	v_exp_f32_e32 v213, v213
	v_add_f32_e32 v141, v141, v212
	v_add_f32_e32 v141, v141, v213
	v_cvt_pk_bf16_f32 v155, v212, v213
	s_waitcnt lgkmcnt(0)
	v_bfe_i32 v60, v226, 16, 1
	v_fmac_f32_e32 v214, 0x3e38aa3b, v186
	v_bitop3_b32 v214, v214, s52, v60 bitop3:0xe4
	v_mfma_f32_32x32x16_bf16 v[16:31], v[222:225], v[152:155], v[16:31]
	v_exp_f32_e32 v214, v214
	v_bfe_i32 v61, v226, 17, 1
	v_fmac_f32_e32 v215, 0x3e38aa3b, v187
	v_bitop3_b32 v215, v215, s52, v61 bitop3:0xe4
	v_exp_f32_e32 v215, v215
	v_add_f32_e32 v141, v141, v214
	v_bfe_i32 v60, v226, 18, 1
	v_fmac_f32_e32 v216, 0x3e38aa3b, v188
	v_bitop3_b32 v216, v216, s52, v60 bitop3:0xe4
	v_exp_f32_e32 v216, v216
	v_add_f32_e32 v141, v141, v215
	v_cvt_pk_bf16_f32 v198, v214, v215
	v_bfe_i32 v61, v226, 19, 1
	v_mfma_f32_32x32x16_bf16 v[0:15], v[252:255], v[152:155], v[0:15]
	ds_read_b128 v[48:51], v137 offset:13824
	ds_read_b128 v[52:55], v137 offset:13856
	ds_read_b128 v[56:59], v137 offset:13888
	ds_read_b128 v[148:151], v137 offset:13920
	ds_read2_b32 v[206:207], v227 offset0:64 offset1:65
	ds_read2_b32 v[208:209], v227 offset0:66 offset1:67
	ds_read2_b32 v[210:211], v227 offset0:72 offset1:73
	ds_read2_b32 v[212:213], v227 offset0:74 offset1:75
	v_fmac_f32_e32 v217, 0x3e38aa3b, v189
	v_bitop3_b32 v217, v217, s52, v61 bitop3:0xe4
	v_exp_f32_e32 v217, v217
	v_add_f32_e32 v141, v141, v216
	v_bfe_i32 v60, v226, 24, 1
	v_fmac_f32_e32 v218, 0x3e38aa3b, v190
	v_bitop3_b32 v218, v218, s52, v60 bitop3:0xe4
	v_exp_f32_e32 v218, v218
	v_add_f32_e32 v141, v141, v217
	v_cvt_pk_bf16_f32 v199, v216, v217
	v_bfe_i32 v61, v226, 25, 1
	v_fmac_f32_e32 v219, 0x3e38aa3b, v191
	v_bitop3_b32 v219, v219, s52, v61 bitop3:0xe4
	v_exp_f32_e32 v219, v219
	v_add_f32_e32 v141, v141, v218
	v_bfe_i32 v60, v226, 26, 1
	v_fmac_f32_e32 v220, 0x3e38aa3b, v192
	v_bitop3_b32 v220, v220, s52, v60 bitop3:0xe4
	v_exp_f32_e32 v220, v220
	v_add_f32_e32 v141, v141, v219
	v_cvt_pk_bf16_f32 v200, v218, v219
	v_bfe_i32 v61, v226, 27, 1
	v_fmac_f32_e32 v221, 0x3e38aa3b, v193
	v_bitop3_b32 v221, v221, s52, v61 bitop3:0xe4
	v_exp_f32_e32 v221, v221
	v_add_f32_e32 v141, v141, v220
	v_add_f32_e32 v141, v141, v221
	v_cvt_pk_bf16_f32 v201, v220, v221
	s_nop 1
	v_mfma_f32_32x32x16_bf16 v[16:31], v[194:197], v[198:201], v[16:31]
	v_mfma_f32_32x32x16_bf16 v[0:15], v[170:173], v[198:201], v[0:15]
	ds_read_b64_tr_b16 v[222:223], v228 offset:46080
	ds_read_b64_tr_b16 v[224:225], v228 offset:47232
	ds_read_b64_tr_b16 v[252:253], v228 offset:46144
	ds_read_b64_tr_b16 v[254:255], v228 offset:47296
	ds_read_b64_tr_b16 v[194:195], v228 offset:48384
	ds_read_b64_tr_b16 v[196:197], v228 offset:49536
	ds_read_b64_tr_b16 v[170:171], v228 offset:48448
	ds_read_b64_tr_b16 v[172:173], v228 offset:49600
	ds_read2_b32 v[214:215], v227 offset0:80 offset1:81
	ds_read2_b32 v[216:217], v227 offset0:82 offset1:83
	ds_read2_b32 v[218:219], v227 offset0:88 offset1:89
	ds_read2_b32 v[220:221], v227 offset0:90 offset1:91
	v_lshrrev_b32_e32 v226, v160, v102
	s_waitcnt lgkmcnt(12)
; #define LAS __attribute__((address_space(3)))
; #define MFMA32(a, b, c) __builtin_amdgcn_mfma_f32_32x32x16_bf16((a), (b), (c), 0, 0, 0)
; DI float ex2(float x) { return __builtin_amdgcn_exp2f(x); }
; template <int D, int STR>
; DI void pv_tile(f32x16* acc, LAS const unsigned char* Vs, int vrow0, bf16x8 p0, bf16x8 p1, int lane) {
;     const int hf = lane >> 5, q = (lane & 15) >> 2, p = lane & 3, blk = (lane >> 4) & 1;
;     LAS const char* vb = (LAS const char*)Vs + (vrow0 + 4 * hf + q) * STR + blk * 32 + p * 8;
; #pragma unroll
;     for (int eb = 0; eb < D / 32; ++eb) {
;         const s16x4 l0 = vtr(vb + eb * 64), h0 = vtr(vb + 8 * STR + eb * 64);
;         const s16x4 l1 = vtr(vb + 16 * STR + eb * 64), h1 = vtr(vb + 24 * STR + eb * 64);
;         const bf16x8 v0 = __builtin_shufflevector(l0, h0, 0, 1, 2, 3, 4, 5, 6, 7), v1 = __builtin_shufflevector(l1, h1, 0, 1, 2, 3, 4, 5, 6, 7);
;         acc[eb] = MFMA32(v0, p0, acc[eb]); acc[eb] = MFMA32(v1, p1, acc[eb]);
;     }
; }
; DI void dsa_unit(Frame& F, int b, int h, int qb) {
;     ...
;         for (int kt = 0; kt < 4; ++kt) {
;             const int s0 = 128 * j + 32 * kt;
;             if (s0 > tw + 31) continue;
;             const unsigned mws = mw4[kt] >> (4 * hf);
;             f32x16 x = st_tile<64, KSTR64>(Ks, 32 * kt, qf, tl, hf);
;             const LAS float* tp = tb + (4095 - (t - s0 - 4 * hf));
;             if (noshift) {
; #pragma unroll
;                 for (int i = 0; i < 16; ++i) {
;                     const int ci = (i & 3) + 8 * (i >> 2);
;                     const unsigned mm = (unsigned)__builtin_amdgcn_sbfe((int)mws, ci, 1);
;                     x[i] = ex2(bfi_f(mm, x[i] * C_D64 + tp[ci], -INFINITY));
;                     l += x[i];
;                 }
;             } else {
; #pragma unroll
;                 for (int i = 0; i < 16; ++i) {
;                     const int ci = (i & 3) + 8 * (i >> 2);
;                     const unsigned mm = (unsigned)__builtin_amdgcn_sbfe((int)mws, ci, 1);
;                     x[i] = ex2(bfi_f(mm, x[i] * C_D64 + tp[ci], -INFINITY) - S);
;                     l += x[i];
;                 }
;             }
;             const bf16x8 p0 = pack8(x, 0), p1 = pack8(x, 1);
;             pv_tile<64, VSTR64>(acc, Vs, 32 * kt, p0, p1, lane);
	v_bfe_i32 v60, v226, 0, 1
	v_fmac_f32_e32 v206, 0x3e38aa3b, v32
	v_bitop3_b32 v206, v206, s52, v60 bitop3:0xe4
	v_exp_f32_e32 v206, v206
	v_mfma_f32_32x32x16_bf16 v[178:193], v[48:51], v[64:67], 0
	v_bfe_i32 v61, v226, 1, 1
	v_fmac_f32_e32 v207, 0x3e38aa3b, v33
	v_bitop3_b32 v207, v207, s52, v61 bitop3:0xe4
	v_exp_f32_e32 v207, v207
	v_add_f32_e32 v141, v141, v206
	v_bfe_i32 v60, v226, 2, 1
	v_fmac_f32_e32 v208, 0x3e38aa3b, v34
	v_bitop3_b32 v208, v208, s52, v60 bitop3:0xe4
	v_exp_f32_e32 v208, v208
	v_add_f32_e32 v141, v141, v207
	v_mfma_f32_32x32x16_bf16 v[178:193], v[52:55], v[68:71], v[178:193]
	v_cvt_pk_bf16_f32 v152, v206, v207
	v_bfe_i32 v61, v226, 3, 1
	v_fmac_f32_e32 v209, 0x3e38aa3b, v35
	v_bitop3_b32 v209, v209, s52, v61 bitop3:0xe4
	v_exp_f32_e32 v209, v209
	v_add_f32_e32 v141, v141, v208
	v_bfe_i32 v60, v226, 8, 1
	v_fmac_f32_e32 v210, 0x3e38aa3b, v36
	v_bitop3_b32 v210, v210, s52, v60 bitop3:0xe4
	v_exp_f32_e32 v210, v210
	v_mfma_f32_32x32x16_bf16 v[178:193], v[56:59], v[72:75], v[178:193]
	v_add_f32_e32 v141, v141, v209
	v_cvt_pk_bf16_f32 v153, v208, v209
	v_bfe_i32 v61, v226, 9, 1
	v_fmac_f32_e32 v211, 0x3e38aa3b, v37
	v_bitop3_b32 v211, v211, s52, v61 bitop3:0xe4
	v_exp_f32_e32 v211, v211
	v_add_f32_e32 v141, v141, v210
	v_bfe_i32 v60, v226, 10, 1
	v_fmac_f32_e32 v212, 0x3e38aa3b, v38
	v_bitop3_b32 v212, v212, s52, v60 bitop3:0xe4
	v_mfma_f32_32x32x16_bf16 v[178:193], v[148:151], v[76:79], v[178:193]
	v_exp_f32_e32 v212, v212
	v_add_f32_e32 v141, v141, v211
	v_cvt_pk_bf16_f32 v154, v210, v211
	v_bfe_i32 v61, v226, 11, 1
	v_fmac_f32_e32 v213, 0x3e38aa3b, v39
	v_bitop3_b32 v213, v213, s52, v61 bitop3:0xe4
	v_exp_f32_e32 v213, v213
	v_add_f32_e32 v141, v141, v212
	v_add_f32_e32 v141, v141, v213
	v_cvt_pk_bf16_f32 v155, v212, v213
	s_waitcnt lgkmcnt(0)
	v_bfe_i32 v60, v226, 16, 1
	v_fmac_f32_e32 v214, 0x3e38aa3b, v40
	v_bitop3_b32 v214, v214, s52, v60 bitop3:0xe4
	v_mfma_f32_32x32x16_bf16 v[16:31], v[222:225], v[152:155], v[16:31]
	v_exp_f32_e32 v214, v214
	v_bfe_i32 v61, v226, 17, 1
	v_fmac_f32_e32 v215, 0x3e38aa3b, v41
	v_bitop3_b32 v215, v215, s52, v61 bitop3:0xe4
	v_exp_f32_e32 v215, v215
	v_add_f32_e32 v141, v141, v214
	v_bfe_i32 v60, v226, 18, 1
	v_fmac_f32_e32 v216, 0x3e38aa3b, v42
	v_bitop3_b32 v216, v216, s52, v60 bitop3:0xe4
	v_exp_f32_e32 v216, v216
	v_add_f32_e32 v141, v141, v215
	v_cvt_pk_bf16_f32 v198, v214, v215
	v_bfe_i32 v61, v226, 19, 1
	v_mfma_f32_32x32x16_bf16 v[0:15], v[252:255], v[152:155], v[0:15]
	ds_read2_b32 v[206:207], v227 offset0:96 offset1:97
	ds_read2_b32 v[208:209], v227 offset0:98 offset1:99
	ds_read2_b32 v[210:211], v227 offset0:104 offset1:105
	ds_read2_b32 v[212:213], v227 offset0:106 offset1:107
	v_fmac_f32_e32 v217, 0x3e38aa3b, v43
	v_bitop3_b32 v217, v217, s52, v61 bitop3:0xe4
	v_exp_f32_e32 v217, v217
	v_add_f32_e32 v141, v141, v216
	v_bfe_i32 v60, v226, 24, 1
	v_fmac_f32_e32 v218, 0x3e38aa3b, v44
	v_bitop3_b32 v218, v218, s52, v60 bitop3:0xe4
	v_exp_f32_e32 v218, v218
	v_add_f32_e32 v141, v141, v217
	v_cvt_pk_bf16_f32 v199, v216, v217
	v_bfe_i32 v61, v226, 25, 1
	v_fmac_f32_e32 v219, 0x3e38aa3b, v45
	v_bitop3_b32 v219, v219, s52, v61 bitop3:0xe4
	v_exp_f32_e32 v219, v219
	v_add_f32_e32 v141, v141, v218
	v_bfe_i32 v60, v226, 26, 1
	v_fmac_f32_e32 v220, 0x3e38aa3b, v46
	v_bitop3_b32 v220, v220, s52, v60 bitop3:0xe4
	v_exp_f32_e32 v220, v220
	v_add_f32_e32 v141, v141, v219
	v_cvt_pk_bf16_f32 v200, v218, v219
	v_bfe_i32 v61, v226, 27, 1
	v_fmac_f32_e32 v221, 0x3e38aa3b, v47
	v_bitop3_b32 v221, v221, s52, v61 bitop3:0xe4
	v_exp_f32_e32 v221, v221
	v_add_f32_e32 v141, v141, v220
	v_add_f32_e32 v141, v141, v221
	v_cvt_pk_bf16_f32 v201, v220, v221
	s_nop 1
	v_mfma_f32_32x32x16_bf16 v[16:31], v[194:197], v[198:201], v[16:31]
	v_mfma_f32_32x32x16_bf16 v[0:15], v[170:173], v[198:201], v[0:15]
	ds_read_b64_tr_b16 v[222:223], v228 offset:50688
	ds_read_b64_tr_b16 v[224:225], v228 offset:51840
	ds_read_b64_tr_b16 v[252:253], v228 offset:50752
	ds_read_b64_tr_b16 v[254:255], v228 offset:51904
	ds_read_b64_tr_b16 v[194:195], v228 offset:52992
	ds_read_b64_tr_b16 v[196:197], v228 offset:54144
	ds_read_b64_tr_b16 v[170:171], v228 offset:53056
	ds_read_b64_tr_b16 v[172:173], v228 offset:54208
	ds_read2_b32 v[214:215], v227 offset0:112 offset1:113
	ds_read2_b32 v[216:217], v227 offset0:114 offset1:115
	ds_read2_b32 v[218:219], v227 offset0:120 offset1:121
	ds_read2_b32 v[220:221], v227 offset0:122 offset1:123
	v_lshrrev_b32_e32 v226, v160, v103
	s_waitcnt lgkmcnt(12)
; DI float ex2(float x) { return __builtin_amdgcn_exp2f(x); }
; DI float bfi_f(unsigned m, float a, float b) { return __uint_as_float((__float_as_uint(a) & m) | (__float_as_uint(b) & ~m)); }
; DI void dsa_unit(Frame& F, int b, int h, int qb) {
;     ...
;             if (noshift) {
; #pragma unroll
;                 for (int i = 0; i < 16; ++i) {
;                     const int ci = (i & 3) + 8 * (i >> 2);
;                     const unsigned mm = (unsigned)__builtin_amdgcn_sbfe((int)mws, ci, 1);
;                     x[i] = ex2(bfi_f(mm, x[i] * C_D64 + tp[ci], -INFINITY));
;                     l += x[i];
;                 }
;             } else {
; #pragma unroll
;                 for (int i = 0; i < 16; ++i) {
;                     const int ci = (i & 3) + 8 * (i >> 2);
;                     const unsigned mm = (unsigned)__builtin_amdgcn_sbfe((int)mws, ci, 1);
;                     x[i] = ex2(bfi_f(mm, x[i] * C_D64 + tp[ci], -INFINITY) - S);
;                     l += x[i];
;                 }
;             }
;             const bf16x8 p0 = pack8(x, 0), p1 = pack8(x, 1);
;             pv_tile<64, VSTR64>(acc, Vs, 32 * kt, p0, p1, lane);
	v_bfe_i32 v60, v226, 0, 1
	v_fmac_f32_e32 v206, 0x3e38aa3b, v178
	v_bitop3_b32 v206, v206, s52, v60 bitop3:0xe4
	v_exp_f32_e32 v206, v206
	v_bfe_i32 v61, v226, 1, 1
	v_fmac_f32_e32 v207, 0x3e38aa3b, v179
	v_bitop3_b32 v207, v207, s52, v61 bitop3:0xe4
	v_exp_f32_e32 v207, v207
	v_add_f32_e32 v141, v141, v206
	v_bfe_i32 v60, v226, 2, 1
	v_fmac_f32_e32 v208, 0x3e38aa3b, v180
	v_bitop3_b32 v208, v208, s52, v60 bitop3:0xe4
	v_exp_f32_e32 v208, v208
	v_add_f32_e32 v141, v141, v207
	v_cvt_pk_bf16_f32 v152, v206, v207
	v_bfe_i32 v61, v226, 3, 1
	v_fmac_f32_e32 v209, 0x3e38aa3b, v181
	v_bitop3_b32 v209, v209, s52, v61 bitop3:0xe4
	v_exp_f32_e32 v209, v209
	v_add_f32_e32 v141, v141, v208
	v_bfe_i32 v60, v226, 8, 1
	v_fmac_f32_e32 v210, 0x3e38aa3b, v182
	v_bitop3_b32 v210, v210, s52, v60 bitop3:0xe4
	v_exp_f32_e32 v210, v210
	v_add_f32_e32 v141, v141, v209
	v_cvt_pk_bf16_f32 v153, v208, v209
	v_bfe_i32 v61, v226, 9, 1
	v_fmac_f32_e32 v211, 0x3e38aa3b, v183
	v_bitop3_b32 v211, v211, s52, v61 bitop3:0xe4
	v_exp_f32_e32 v211, v211
	v_add_f32_e32 v141, v141, v210
	v_bfe_i32 v60, v226, 10, 1
	v_fmac_f32_e32 v212, 0x3e38aa3b, v184
	v_bitop3_b32 v212, v212, s52, v60 bitop3:0xe4
	v_exp_f32_e32 v212, v212
	v_add_f32_e32 v141, v141, v211
	v_cvt_pk_bf16_f32 v154, v210, v211
	v_bfe_i32 v61, v226, 11, 1
	v_fmac_f32_e32 v213, 0x3e38aa3b, v185
	v_bitop3_b32 v213, v213, s52, v61 bitop3:0xe4
	v_exp_f32_e32 v213, v213
	v_add_f32_e32 v141, v141, v212
	v_add_f32_e32 v141, v141, v213
	v_cvt_pk_bf16_f32 v155, v212, v213
	s_waitcnt lgkmcnt(0)
	v_bfe_i32 v60, v226, 16, 1
	v_fmac_f32_e32 v214, 0x3e38aa3b, v186
	v_bitop3_b32 v214, v214, s52, v60 bitop3:0xe4
	v_mfma_f32_32x32x16_bf16 v[16:31], v[222:225], v[152:155], v[16:31]
	v_exp_f32_e32 v214, v214
	v_bfe_i32 v61, v226, 17, 1
	v_fmac_f32_e32 v215, 0x3e38aa3b, v187
	v_bitop3_b32 v215, v215, s52, v61 bitop3:0xe4
	v_exp_f32_e32 v215, v215
	v_add_f32_e32 v141, v141, v214
	v_bfe_i32 v60, v226, 18, 1
	v_fmac_f32_e32 v216, 0x3e38aa3b, v188
	v_bitop3_b32 v216, v216, s52, v60 bitop3:0xe4
	v_exp_f32_e32 v216, v216
	v_add_f32_e32 v141, v141, v215
	v_cvt_pk_bf16_f32 v198, v214, v215
	v_bfe_i32 v61, v226, 19, 1
	v_mfma_f32_32x32x16_bf16 v[0:15], v[252:255], v[152:155], v[0:15]
	v_fmac_f32_e32 v217, 0x3e38aa3b, v189
	v_bitop3_b32 v217, v217, s52, v61 bitop3:0xe4
	v_exp_f32_e32 v217, v217
	v_add_f32_e32 v141, v141, v216
	v_bfe_i32 v60, v226, 24, 1
	v_fmac_f32_e32 v218, 0x3e38aa3b, v190
	v_bitop3_b32 v218, v218, s52, v60 bitop3:0xe4
	v_exp_f32_e32 v218, v218
	v_add_f32_e32 v141, v141, v217
	v_cvt_pk_bf16_f32 v199, v216, v217
	v_bfe_i32 v61, v226, 25, 1
	v_fmac_f32_e32 v219, 0x3e38aa3b, v191
	v_bitop3_b32 v219, v219, s52, v61 bitop3:0xe4
	v_exp_f32_e32 v219, v219
	v_add_f32_e32 v141, v141, v218
	v_bfe_i32 v60, v226, 26, 1
	v_fmac_f32_e32 v220, 0x3e38aa3b, v192
	v_bitop3_b32 v220, v220, s52, v60 bitop3:0xe4
	v_exp_f32_e32 v220, v220
	v_add_f32_e32 v141, v141, v219
	v_cvt_pk_bf16_f32 v200, v218, v219
	v_bfe_i32 v61, v226, 27, 1
	v_fmac_f32_e32 v221, 0x3e38aa3b, v193
	v_bitop3_b32 v221, v221, s52, v61 bitop3:0xe4
	v_exp_f32_e32 v221, v221
	v_add_f32_e32 v141, v141, v220
	v_add_f32_e32 v141, v141, v221
	v_cvt_pk_bf16_f32 v201, v220, v221
	s_nop 1
	v_mfma_f32_32x32x16_bf16 v[16:31], v[194:197], v[198:201], v[16:31]
	v_mfma_f32_32x32x16_bf16 v[0:15], v[170:173], v[198:201], v[0:15]
	s_branch .LBB0_519

; __global__ void __launch_bounds__(NTHR, 2) fwd(Args args) {
;     extern __shared__ __attribute__((aligned(16))) unsigned char lds_raw[];
	.amdhsa_kernel _Z3fwd4Args
		.amdhsa_group_segment_fixed_size 0
		.amdhsa_private_segment_fixed_size 0
		.amdhsa_kernarg_size 376
		.amdhsa_user_sgpr_count 2
		.amdhsa_user_sgpr_dispatch_ptr 0
		.amdhsa_user_sgpr_queue_ptr 0
		.amdhsa_user_sgpr_kernarg_segment_ptr 1
		.amdhsa_user_sgpr_dispatch_id 0
		.amdhsa_user_sgpr_kernarg_preload_length 0
		.amdhsa_user_sgpr_kernarg_preload_offset 0
		.amdhsa_user_sgpr_private_segment_size 0
		.amdhsa_uses_dynamic_stack 0
		.amdhsa_enable_private_segment 0
		.amdhsa_system_sgpr_workgroup_id_x 1
		.amdhsa_system_sgpr_workgroup_id_y 0
		.amdhsa_system_sgpr_workgroup_id_z 0
		.amdhsa_system_sgpr_workgroup_info 0
		.amdhsa_system_vgpr_workitem_id 2
		.amdhsa_next_free_vgpr 256
		.amdhsa_next_free_sgpr 102
		.amdhsa_accum_offset 256
		.amdhsa_reserve_vcc 1
		.amdhsa_float_round_mode_32 0
		.amdhsa_float_round_mode_16_64 0
		.amdhsa_float_denorm_mode_32 3
		.amdhsa_float_denorm_mode_16_64 3
		.amdhsa_dx10_clamp 1
		.amdhsa_ieee_mode 1
		.amdhsa_fp16_overflow 0
		.amdhsa_tg_split 0
		.amdhsa_exception_fp_ieee_invalid_op 0
		.amdhsa_exception_fp_denorm_src 0
		.amdhsa_exception_fp_ieee_div_zero 0
		.amdhsa_exception_fp_ieee_overflow 0
		.amdhsa_exception_fp_ieee_underflow 0
		.amdhsa_exception_fp_ieee_inexact 0
		.amdhsa_exception_int_div_zero 0
	.end_amdhsa_kernel

; __global__ void __launch_bounds__(NTHR, 2) fwd(Args args) {
;     extern __shared__ __attribute__((aligned(16))) unsigned char lds_raw[];
.Lfunc_end0:
	.size	_Z3fwd4Args, .Lfunc_end0-_Z3fwd4Args
	.set _Z3fwd4Args.num_vgpr, 256
	.set _Z3fwd4Args.num_agpr, 0
	.set _Z3fwd4Args.numbered_sgpr, 102
	.set _Z3fwd4Args.num_named_barrier, 0
	.set _Z3fwd4Args.private_seg_size, 0
	.set _Z3fwd4Args.uses_vcc, 1
	.set _Z3fwd4Args.uses_flat_scratch, 0
	.set _Z3fwd4Args.has_dyn_sized_stack, 0
	.set _Z3fwd4Args.has_recursion, 0
	.set _Z3fwd4Args.has_indirect_call, 0

; __global__ void __launch_bounds__(NTHR, 2) fwd(Args args) {
;     extern __shared__ __attribute__((aligned(16))) unsigned char lds_raw[];
amdhsa.kernels:
  - .agpr_count:     0
    .args:
      - .offset:         0
        .size:           120
        .value_kind:     by_value
      - .offset:         120
        .size:           4
        .value_kind:     hidden_block_count_x
      - .offset:         124
        .size:           4
        .value_kind:     hidden_block_count_y
      - .offset:         128
        .size:           4
        .value_kind:     hidden_block_count_z
      - .offset:         132
        .size:           2
        .value_kind:     hidden_group_size_x
      - .offset:         134
        .size:           2
        .value_kind:     hidden_group_size_y
      - .offset:         136
        .size:           2
        .value_kind:     hidden_group_size_z
      - .offset:         138
        .size:           2
        .value_kind:     hidden_remainder_x
      - .offset:         140
        .size:           2
        .value_kind:     hidden_remainder_y
      - .offset:         142
        .size:           2
        .value_kind:     hidden_remainder_z
      - .offset:         160
        .size:           8
        .value_kind:     hidden_global_offset_x
      - .offset:         168
        .size:           8
        .value_kind:     hidden_global_offset_y
      - .offset:         176
        .size:           8
        .value_kind:     hidden_global_offset_z
      - .offset:         184
        .size:           2
        .value_kind:     hidden_grid_dims
      - .offset:         208
        .size:           8
        .value_kind:     hidden_multigrid_sync_arg
      - .offset:         240
        .size:           4
        .value_kind:     hidden_dynamic_lds_size
    .group_segment_fixed_size: 0
    .kernarg_segment_align: 8
    .kernarg_segment_size: 376
    .language:       OpenCL C
    .language_version:
      - 2
      - 0
    .max_flat_workgroup_size: 512
    .name:           _Z3fwd4Args
    .private_segment_fixed_size: 0
    .sgpr_count:     108
    .sgpr_spill_count: 166
    .symbol:         _Z3fwd4Args.kd
    .uniform_work_group_size: 1
    .uses_dynamic_stack: false
    .vgpr_count:     256
    .vgpr_spill_count: 0
    .wavefront_size: 64
